# combo4: redundant vmcnt(0) waits removed (P1 K-loop top, k/vs epilogues); loads batched up front in the P2 prompt-item epilogue and prologue and in the P3/P4 sample-row tiles
# baseline (speedup 1.0000x reference)
; #define UNROLL _Pragma("unroll")
; __device__ __forceinline__ void p4_sample(const Params& P, LAS unsigned char* lds) {
;     ...
;     for (int T = blockIdx.x * 2 + slot; T < 512; T += gridDim.x * 2) {
;         const int r0 = MP + 16 * (T >> 6), c0 = 16 * (T & 63);
;         const bf16_t* A = (const bf16_t*)(ws + WS_HB) + (size_t)(r0 + fr) * 1024 + 256 * kq + 8 * fq;
;         const bf16_t* B = (const bf16_t*)(ws + WS_WG) + (size_t)(c0 + fr) * 1024 + 256 * kq + 8 * fq;
;         const bf16_t* A2 = (const bf16_t*)(ws + WS_PB) + (size_t)(r0 + fr) * 256 + 64 * kq + 8 * fq;
;         const bf16_t* B2 = (const bf16_t*)(ws + WS_WP) + (size_t)(c0 + fr) * 256 + 64 * kq + 8 * fq;
;         bf16x8 a[8], b[8], a2[2], b2[2];
;         UNROLL for (int i = 0; i < 8; ++i) { a[i] = *(const bf16x8*)(A + 32 * i); b[i] = *(const bf16x8*)(B + 32 * i); }
;         UNROLL for (int i = 0; i < 2; ++i) { a2[i] = *(const bf16x8*)(A2 + 32 * i); b2[i] = *(const bf16x8*)(B2 + 32 * i); }
;         f32x4 acc = (f32x4){0.f, 0.f, 0.f, 0.f}, acc2 = acc;
;         UNROLL for (int i = 0; i < 8; ++i) acc = MFMA16(b[i], a[i], acc);
;         UNROLL for (int i = 0; i < 2; ++i) acc2 = MFMA16(b2[i], a2[i], acc2);
;         red[((slot * 4 + kq) * 2) * 64 + lane] = acc; red[((slot * 4 + kq) * 2 + 1) * 64 + lane] = acc2;
;         __syncthreads();
;         if (kq == 0) {
;             f32x4 g = (f32x4){0.f, 0.f, 0.f, 0.f}, pp = g;
;             UNROLL for (int q = 0; q < 4; ++q) { g = g + red[((slot * 4 + q) * 2) * 64 + lane]; pp = pp + red[((slot * 4 + q) * 2 + 1) * 64 + lane]; }
;             const int r = r0 + fr, c = c0 + 4 * fq;
;             const float* sq = (const float*)(ws + WS_SSQS) + (r - MP) * 64 + 16 * fq;
;             float t = 0.f;
;             UNROLL for (int q = 0; q < 4; ++q) { const f32x4 v = *(const f32x4*)(sq + 4 * q); t += (v.x + v.y) + (v.z + v.w); }
;             t += __shfl_xor(t, 16); t += __shfl_xor(t, 32);
;             const float rstd = rsqrtf(t * (1.f / 1024.f) + EPS);
;             float* yp = P.out + (size_t)r * 1024 + c;
;             const u32x2 hw = *(const u32x2*)((const bf16_t*)(ws + WS_HB) + (size_t)r * 1024 + c);
;             const f32x4 hv = (f32x4){bflo(hw.x), bfhi(hw.x), bflo(hw.y), bfhi(hw.y)};
;             f32x4 y;
;             UNROLL for (int j = 0; j < 4; ++j) y[j] = hv[j] + sigmoid_f(g[j] * rstd) * pp[j];
;             *(f32x4*)yp = y;
;         }
.LBB0_1027:
	v_ashrrev_i32_e32 v0, 2, v18
	v_and_b32_e32 v31, 0x3f0, v23
	v_and_b32_e32 v0, -16, v0
	v_or_b32_e32 v40, v31, v19
	v_add_u32_e32 v14, v0, v20
	v_lshlrev_b32_e32 v0, 11, v40
	v_ashrrev_i32_e32 v15, 31, v14
	v_lshl_add_u64 v[72:73], v[2:3], 0, v[0:1]
	v_lshlrev_b64 v[16:17], 11, v[14:15]
	global_load_dwordx4 v[32:35], v[72:73], off
	v_lshl_add_u64 v[16:17], s[68:69], 0, v[16:17]
	v_lshl_add_u64 v[36:37], v[16:17], 0, v[10:11]
	v_lshl_add_u64 v[74:75], v[36:37], 0, v[12:13]
	global_load_dwordx4 v[36:39], v[74:75], off
	global_load_dwordx4 v[44:47], v[72:73], off offset:64
	v_lshlrev_b32_e32 v0, 9, v40
	v_lshl_add_u64 v[68:69], v[6:7], 0, v[0:1]
	global_load_dwordx4 v[40:43], v[68:69], off
	v_lshlrev_b64 v[48:49], 9, v[14:15]
	v_lshl_add_u64 v[70:71], v[4:5], 0, v[48:49]
	global_load_dwordx4 v[48:51], v[70:71], off
	global_load_dwordx4 v[52:55], v[68:69], off offset:64
	global_load_dwordx4 v[56:59], v[74:75], off offset:64
	global_load_dwordx4 v[60:63], v[72:73], off offset:128
	global_load_dwordx4 v[64:67], v[70:71], off offset:64
	global_load_dwordx4 v[84:87], v[74:75], off offset:128
	global_load_dwordx4 v[88:91], v[72:73], off offset:192
	global_load_dwordx4 v[92:95], v[74:75], off offset:192
	global_load_dwordx4 v[96:99], v[72:73], off offset:256
	global_load_dwordx4 v[100:103], v[72:73], off offset:320
	global_load_dwordx4 v[104:107], v[74:75], off offset:256
	global_load_dwordx4 v[108:111], v[74:75], off offset:320
	global_load_dwordx4 v[112:115], v[72:73], off offset:384
	global_load_dwordx4 v[116:119], v[72:73], off offset:448
	global_load_dwordx4 v[120:123], v[74:75], off offset:384
	global_load_dwordx4 v[124:127], v[74:75], off offset:448
	s_waitcnt vmcnt(18)
	v_mfma_f32_16x16x32_bf16 v[32:35], v[32:35], v[36:39], 0
	s_waitcnt vmcnt(15)
	v_mfma_f32_16x16x32_bf16 v[40:43], v[40:43], v[48:51], 0
	s_waitcnt vmcnt(13)
	v_mfma_f32_16x16x32_bf16 v[32:35], v[44:47], v[56:59], v[32:35]
	s_waitcnt vmcnt(11)
	v_mfma_f32_16x16x32_bf16 v[40:43], v[52:55], v[64:67], v[40:43]
	s_waitcnt vmcnt(10)
	v_mfma_f32_16x16x32_bf16 v[32:35], v[60:63], v[84:87], v[32:35]
	s_waitcnt vmcnt(8)
	v_mfma_f32_16x16x32_bf16 v[32:35], v[88:91], v[92:95], v[32:35]
	s_waitcnt vmcnt(5)
	v_mfma_f32_16x16x32_bf16 v[32:35], v[96:99], v[104:107], v[32:35]
	s_waitcnt vmcnt(4)
	v_mfma_f32_16x16x32_bf16 v[32:35], v[100:103], v[108:111], v[32:35]
	ds_write_b128 v24, v[40:43] offset:1024
	s_waitcnt vmcnt(1)
	v_mfma_f32_16x16x32_bf16 v[32:35], v[112:115], v[120:123], v[32:35]
	s_waitcnt vmcnt(0)
	v_mfma_f32_16x16x32_bf16 v[32:35], v[116:119], v[124:127], v[32:35]
	s_nop 7
	ds_write_b128 v24, v[32:35]
	s_waitcnt lgkmcnt(0)
	s_barrier
	s_and_saveexec_b64 s[6:7], vcc
	s_cbranch_execz .LBB0_1026
	v_lshl_add_u32 v32, v14, 6, v26
	v_ashrrev_i32_e32 v33, 31, v32
	v_lshl_add_u64 v[48:49], v[32:33], 2, v[8:9]
	global_load_dwordx4 v[32:35], v[48:49], off
	global_load_dwordx4 v[36:39], v[48:49], off offset:16
	global_load_dwordx4 v[40:43], v[48:49], off offset:32
	global_load_dwordx4 v[44:47], v[48:49], off offset:48
	v_or_b32_e32 v31, v31, v22
	v_lshlrev_b32_e32 v0, 1, v31
	v_lshl_add_u64 v[16:17], v[16:17], 0, v[0:1]
	global_load_dwordx2 v[76:77], v[16:17], off
	v_lshlrev_b64 v[78:79], 10, v[14:15]
	ds_read_b128 v[14:17], v21
	ds_read_b128 v[48:51], v21 offset:1024
	ds_read_b128 v[52:55], v21 offset:2048
	ds_read_b128 v[56:59], v21 offset:3072
	ds_read_b128 v[60:63], v21 offset:4096
	ds_read_b128 v[64:67], v21 offset:5120
	ds_read_b128 v[68:71], v21 offset:6144
	ds_read_b128 v[72:75], v21 offset:7168
	s_waitcnt lgkmcnt(7)
	v_pk_add_f32 v[16:17], v[16:17], 0 op_sel_hi:[1,0]
	v_cmp_lt_i32_e64 s[0:1], v28, v29
	s_waitcnt lgkmcnt(5)
	v_pk_add_f32 v[16:17], v[16:17], v[54:55]
	v_pk_add_f32 v[14:15], v[14:15], 0 op_sel_hi:[1,0]
	v_cndmask_b32_e64 v0, v27, v28, s[0:1]
	v_lshlrev_b32_e32 v81, 2, v0
	v_lshlrev_b32_e32 v0, 2, v31
	v_cmp_lt_i32_e64 s[0:1], v30, v29
	v_pk_add_f32 v[14:15], v[14:15], v[52:53]
	s_waitcnt lgkmcnt(3)
	v_pk_add_f32 v[16:17], v[16:17], v[62:63]
	v_cndmask_b32_e64 v80, v27, v30, s[0:1]
	v_lshlrev_b32_e32 v80, 2, v80
	v_pk_add_f32 v[14:15], v[14:15], v[60:61]
	s_waitcnt lgkmcnt(1)
	v_pk_add_f32 v[16:17], v[16:17], v[70:71]
	v_pk_add_f32 v[14:15], v[14:15], v[68:69]
	v_pk_add_f32 v[50:51], v[50:51], 0 op_sel_hi:[1,0]
	v_pk_add_f32 v[48:49], v[48:49], 0 op_sel_hi:[1,0]
	v_pk_add_f32 v[50:51], v[50:51], v[58:59]
	v_pk_add_f32 v[48:49], v[48:49], v[56:57]
	v_lshl_add_u64 v[78:79], v[78:79], 2, s[66:67]
	s_waitcnt vmcnt(4)
	v_mov_b32_e32 v54, v33
	v_mov_b32_e32 v55, v34
	v_mov_b32_e32 v33, v35
	s_waitcnt vmcnt(3)
	v_mov_b32_e32 v34, v37
	v_mov_b32_e32 v35, v38
	v_mov_b32_e32 v37, v39
	v_pk_add_f32 v[32:33], v[54:55], v[32:33]
	v_pk_add_f32 v[34:35], v[34:35], v[36:37]
	v_add_f32_e32 v31, v32, v33
	v_pk_add_f32 v[32:33], v[34:35], v[34:35] op_sel:[0,1] op_sel_hi:[1,0]
	s_waitcnt vmcnt(2)
	v_add_f32_e32 v38, v40, v41
	v_add_f32_e32 v40, v42, v43
	s_waitcnt vmcnt(1)
	v_mov_b32_e32 v43, v44
	v_mov_b32_e32 v39, v46
	v_mov_b32_e32 v41, v47
	v_add_f32_e32 v42, 0, v31
	v_mov_b32_e32 v33, v45
	v_pk_add_f32 v[36:37], v[38:39], v[40:41]
	v_pk_add_f32 v[32:33], v[42:43], v[32:33]
	v_pk_add_f32 v[34:35], v[48:49], v[64:65]
	v_pk_add_f32 v[32:33], v[32:33], v[36:37]
	s_waitcnt lgkmcnt(0)
	v_pk_add_f32 v[34:35], v[34:35], v[72:73]
	v_add_f32_e32 v31, v32, v33
	ds_bpermute_b32 v36, v81, v31
	v_pk_add_f32 v[32:33], v[50:51], v[66:67]
	s_waitcnt vmcnt(0)
	v_and_b32_e32 v37, 0xffff0000, v76
	v_pk_add_f32 v[32:33], v[32:33], v[74:75]
	v_and_b32_e32 v39, 0xffff0000, v77
	s_waitcnt lgkmcnt(0)
	v_add_f32_e32 v31, v31, v36
	ds_bpermute_b32 v36, v80, v31
	s_waitcnt lgkmcnt(0)
	v_add_f32_e32 v31, v31, v36
	v_fmamk_f32 v31, v31, 0x3a800000, v25
	v_mul_f32_e32 v36, 0x4b800000, v31
	v_cmp_gt_f32_e64 s[0:1], s10, v31
	s_nop 1
	v_cndmask_b32_e64 v31, v31, v36, s[0:1]
	v_rsq_f32_e32 v31, v31
	v_lshlrev_b32_e32 v36, 16, v76
	v_mul_f32_e32 v38, 0x45800000, v31
	v_cndmask_b32_e64 v31, v31, v38, s[0:1]
	v_mul_f32_e32 v14, v14, v31
	v_mul_f32_e32 v15, v15, v31
	v_mul_f32_e32 v16, v16, v31
	v_mul_f32_e32 v17, v17, v31
	v_mul_f32_e32 v14, 0xbfb8aa3b, v14
	v_mul_f32_e32 v15, 0xbfb8aa3b, v15
	v_mul_f32_e32 v16, 0xbfb8aa3b, v16
	v_mul_f32_e32 v17, 0xbfb8aa3b, v17
	v_exp_f32_e32 v14, v14
	v_exp_f32_e32 v15, v15
	v_exp_f32_e32 v16, v16
	v_exp_f32_e32 v17, v17
	v_add_f32_e32 v14, 1.0, v14
	v_add_f32_e32 v15, 1.0, v15
	v_add_f32_e32 v16, 1.0, v16
	v_add_f32_e32 v17, 1.0, v17
	v_rcp_f32_e32 v14, v14
	v_rcp_f32_e32 v15, v15
	v_rcp_f32_e32 v16, v16
	v_rcp_f32_e32 v17, v17
	v_lshlrev_b32_e32 v38, 16, v77
	v_pk_fma_f32 v[14:15], v[34:35], v[14:15], v[36:37]
	v_pk_fma_f32 v[16:17], v[32:33], v[16:17], v[38:39]
	v_lshl_add_u64 v[32:33], v[78:79], 0, v[0:1]
	global_store_dwordx4 v[32:33], v[14:17], off
	s_branch .LBB0_1026
